# v41 + next-tile LDS stage writes and K/V/rope global loads moved from the loop top into the QK1 MFMA stream
# speedup vs baseline: 1.0041x; 1.0041x over previous
.LBB0_380:
	s_add_i32 s20, s37, 4
	s_cmp_gt_i32 s20, s35
	s_cbranch_scc1 .Lm_stage_only
	s_bitcmp1_b32 s20, 0
	s_cselect_b32 s38, 0xb400, 0
	v_add_u32_e32 v8, s38, v191
	ds_read_b128 v[10:13], v8
	ds_read_b128 v[14:17], v8 offset:32
	ds_read_b128 v[202:205], v8 offset:64
	ds_read_b128 v[206:209], v8 offset:96
	v_add_u32_e32 v197, s38, v196
	s_setprio 3
	s_waitcnt lgkmcnt(3)
	v_mfma_f32_32x32x16_bf16 v[100:115], v[10:13], v[116:119], v[210:225]
	ds_read_b128 v[10:13], v8 offset:128
	s_waitcnt lgkmcnt(3)
	v_mfma_f32_32x32x16_bf16 v[100:115], v[14:17], v[120:123], v[100:115]
	ds_read_b128 v[14:17], v8 offset:160
	s_add_i32 s21, s37, 5
	s_cmp_ge_i32 s21, s34
	s_cbranch_scc1 .Lm_skw_m
	s_bitcmp1_b32 s21, 0
	s_cselect_b32 s21, 0xb400, 0
	v_add_u32_e32 v2, s21, v188
	s_waitcnt vmcnt(4)
	ds_write_b128 v2, v[128:131]
	s_waitcnt vmcnt(3)
	ds_write_b128 v2, v[168:171] offset:12800
	v_add_u32_e32 v2, s21, v19
	s_waitcnt vmcnt(2)
	ds_write_b128 v2, v[172:175] offset:25600
	s_waitcnt vmcnt(1)
	ds_write_b128 v2, v[180:183] offset:35840
	v_add_u32_e32 v2, s21, v190
	s_waitcnt vmcnt(0)
	ds_write_b128 v2, v[176:179] offset:256
.Lm_skw_m:
	s_waitcnt lgkmcnt(3)
	v_mfma_f32_32x32x16_bf16 v[100:115], v[202:205], v[124:127], v[100:115]
	ds_read_b128 v[202:205], v8 offset:192
	s_waitcnt lgkmcnt(3)
	v_mfma_f32_32x32x16_bf16 v[100:115], v[206:209], v[132:135], v[100:115]
	ds_read_b128 v[206:209], v8 offset:224
	s_waitcnt lgkmcnt(3)
	v_mfma_f32_32x32x16_bf16 v[100:115], v[10:13], v[136:139], v[100:115]
	ds_read_b128 v[10:13], v8 offset:256
	s_waitcnt lgkmcnt(3)
	v_mfma_f32_32x32x16_bf16 v[100:115], v[14:17], v[140:143], v[100:115]
	ds_read_b128 v[14:17], v8 offset:288
	s_add_i32 s21, s37, 4
	s_cmp_ge_i32 s21, s36
	s_cbranch_scc1 .Lm_skl_m
	v_add_u32_e32 v241, 0x10000, v6
	v_add_u32_e32 v242, 0x4000000, v6
	v_add_u32_e32 v243, 0x4010000, v6
	global_load_dwordx4 v[128:131], v6, s[98:99]
	global_load_dwordx4 v[168:171], v241, s[98:99]
	global_load_dwordx4 v[172:175], v242, s[98:99]
	global_load_dwordx4 v[180:183], v243, s[98:99]
	global_load_dwordx4 v[176:179], v4, s[100:101]
.Lm_skl_m:
	s_waitcnt lgkmcnt(3)
	v_mfma_f32_32x32x16_bf16 v[100:115], v[202:205], v[144:147], v[100:115]
	ds_read_b128 v[202:205], v8 offset:320
	s_waitcnt lgkmcnt(3)
	v_mfma_f32_32x32x16_bf16 v[100:115], v[206:209], v[148:151], v[100:115]
	ds_read_b128 v[206:209], v8 offset:352
	s_waitcnt lgkmcnt(3)
	v_mfma_f32_32x32x16_bf16 v[100:115], v[10:13], v[152:155], v[100:115]
	ds_read_b128 v[10:13], v8 offset:12800
	s_waitcnt lgkmcnt(3)
	v_mfma_f32_32x32x16_bf16 v[100:115], v[14:17], v[156:159], v[100:115]
	ds_read_b128 v[14:17], v8 offset:12832
	s_waitcnt lgkmcnt(3)
	v_mfma_f32_32x32x16_bf16 v[100:115], v[202:205], v[160:163], v[100:115]
	ds_read_b128 v[202:205], v8 offset:12864
	s_waitcnt lgkmcnt(3)
	v_mfma_f32_32x32x16_bf16 v[100:115], v[206:209], v[164:167], v[100:115]
	ds_read_b128 v[206:209], v8 offset:12896
	s_waitcnt lgkmcnt(3)
	v_mfma_f32_32x32x16_bf16 v[84:99], v[10:13], v[116:119], v[210:225]
	ds_read_b128 v[10:13], v8 offset:12928
	s_waitcnt lgkmcnt(3)
	v_mfma_f32_32x32x16_bf16 v[84:99], v[14:17], v[120:123], v[84:99]
	ds_read_b128 v[14:17], v8 offset:12960
	s_waitcnt lgkmcnt(3)
	v_mfma_f32_32x32x16_bf16 v[84:99], v[202:205], v[124:127], v[84:99]
	ds_read_b128 v[202:205], v8 offset:12992
	s_waitcnt lgkmcnt(3)
	v_mfma_f32_32x32x16_bf16 v[84:99], v[206:209], v[132:135], v[84:99]
	ds_read_b128 v[206:209], v8 offset:13024
	s_waitcnt lgkmcnt(3)
	v_mfma_f32_32x32x16_bf16 v[84:99], v[10:13], v[136:139], v[84:99]
	ds_read_b128 v[10:13], v8 offset:13056
	v_exp_f32_e32 v100, v100
	v_exp_f32_e32 v101, v101
	s_waitcnt lgkmcnt(3)
	v_mfma_f32_32x32x16_bf16 v[84:99], v[14:17], v[140:143], v[84:99]
	ds_read_b128 v[14:17], v8 offset:13088
	v_exp_f32_e32 v102, v102
	v_exp_f32_e32 v103, v103
	v_add_f32_e32 v234, 0, v100
	v_add_f32_e32 v234, v101, v234
	s_waitcnt lgkmcnt(3)
	v_mfma_f32_32x32x16_bf16 v[84:99], v[202:205], v[144:147], v[84:99]
	ds_read_b128 v[202:205], v8 offset:13120
	v_exp_f32_e32 v104, v104
	v_exp_f32_e32 v105, v105
	v_add_f32_e32 v234, v102, v234
	v_add_f32_e32 v234, v103, v234
	s_waitcnt lgkmcnt(3)
	v_mfma_f32_32x32x16_bf16 v[84:99], v[206:209], v[148:151], v[84:99]
	ds_read_b128 v[206:209], v8 offset:13152
	v_exp_f32_e32 v106, v106
	v_exp_f32_e32 v107, v107
	v_add_f32_e32 v234, v104, v234
	v_add_f32_e32 v234, v105, v234
	s_waitcnt lgkmcnt(3)
	v_mfma_f32_32x32x16_bf16 v[84:99], v[10:13], v[152:155], v[84:99]
	ds_read_b64_tr_b16 v[10:11], v197 offset:25600
	ds_read_b64_tr_b16 v[12:13], v197 offset:28160
	v_exp_f32_e32 v108, v108
	v_exp_f32_e32 v109, v109
	v_add_f32_e32 v234, v106, v234
	v_add_f32_e32 v234, v107, v234
	s_waitcnt lgkmcnt(4)
	v_mfma_f32_32x32x16_bf16 v[84:99], v[14:17], v[156:159], v[84:99]
	ds_read_b64_tr_b16 v[14:15], v197 offset:25664
	ds_read_b64_tr_b16 v[16:17], v197 offset:28224
	v_exp_f32_e32 v110, v110
	v_exp_f32_e32 v111, v111
	v_add_f32_e32 v234, v108, v234
	v_add_f32_e32 v234, v109, v234
	s_waitcnt lgkmcnt(5)
	v_mfma_f32_32x32x16_bf16 v[84:99], v[202:205], v[160:163], v[84:99]
	ds_read_b64_tr_b16 v[202:203], v197 offset:25728
	ds_read_b64_tr_b16 v[204:205], v197 offset:28288
	v_exp_f32_e32 v112, v112
	v_exp_f32_e32 v113, v113
	v_add_f32_e32 v234, v110, v234
	v_add_f32_e32 v234, v111, v234
	s_waitcnt lgkmcnt(6)
	v_mfma_f32_32x32x16_bf16 v[84:99], v[206:209], v[164:167], v[84:99]
	ds_read_b64_tr_b16 v[206:207], v197 offset:25792
	ds_read_b64_tr_b16 v[208:209], v197 offset:28352
	v_exp_f32_e32 v114, v114
	v_exp_f32_e32 v115, v115
	v_add_f32_e32 v234, v112, v234
	v_add_f32_e32 v234, v113, v234
	v_add_f32_e32 v234, v114, v234
	v_add_f32_e32 v234, v115, v234
	s_and_b64 vcc, exec, s[18:19]
	s_cbranch_vccz .Lm_p1
	s_setprio 0
	s_branch .Lm_pd

.Lm_stage_only:
	s_add_i32 s21, s37, 5
	s_cmp_ge_i32 s21, s34
	s_cbranch_scc1 .Lm_skw_s
	s_bitcmp1_b32 s21, 0
	s_cselect_b32 s21, 0xb400, 0
	v_add_u32_e32 v2, s21, v188
	s_waitcnt vmcnt(4)
	ds_write_b128 v2, v[128:131]
	s_waitcnt vmcnt(3)
	ds_write_b128 v2, v[168:171] offset:12800
	v_add_u32_e32 v2, s21, v19
	s_waitcnt vmcnt(2)
	ds_write_b128 v2, v[172:175] offset:25600
	s_waitcnt vmcnt(1)
	ds_write_b128 v2, v[180:183] offset:35840
	v_add_u32_e32 v2, s21, v190
	s_waitcnt vmcnt(0)
	ds_write_b128 v2, v[176:179] offset:256
.Lm_skw_s:
	s_add_i32 s21, s37, 4
	s_cmp_ge_i32 s21, s36
	s_cbranch_scc1 .Lm_skl_s
	v_add_u32_e32 v241, 0x10000, v6
	v_add_u32_e32 v242, 0x4000000, v6
	v_add_u32_e32 v243, 0x4010000, v6
	global_load_dwordx4 v[128:131], v6, s[98:99]
	global_load_dwordx4 v[168:171], v241, s[98:99]
	global_load_dwordx4 v[172:175], v242, s[98:99]
	global_load_dwordx4 v[180:183], v243, s[98:99]
	global_load_dwordx4 v[176:179], v4, s[100:101]
.Lm_skl_s:
	s_branch .LBB0_379
